# top-k phase: logical wave ids of the second half-block rotated by one so the two single-wave candidate stages run on different SIMDs
# speedup vs baseline: 1.0479x; 1.0005x over previous
.LBB0_75:
	s_andn2_b64 vcc, exec, s[20:21]
	s_cbranch_vccnz .LBB0_104
	v_mov_b32_e32 v0, v135
	v_add_u32_e32 v1, 64, v0
	v_and_b32_e32 v1, 0xc0, v1
	v_and_b32_e32 v2, 0xffffff3f, v0
	v_or_b32_e32 v1, v1, v2
	v_cmp_lt_u32_e32 vcc, 0xff, v0
	s_nop 1
	v_cndmask_b32_e32 v0, v0, v1, vcc
	s_nop 0
	s_mov_b32 s63, s80
	v_readfirstlane_b32 s0, v0
	s_ashr_i32 s0, s0, 8
	s_add_i32 s62, s0, s79
	s_mov_b64 s[30:31], 0
	s_cmpk_gt_i32 s62, 0x3ff
	s_cbranch_scc1 .LBB0_104
	v_and_b32_e32 v1, 0xff, v0
	s_movk_i32 s1, 0x80
	s_add_u32 s34, s66, s30
	v_cmp_gt_u32_e32 vcc, s1, v1
	s_addc_u32 s35, s67, s31
	v_and_b32_e32 v6, 31, v0
	v_cndmask_b32_e32 v132, v177, v178, vcc
	v_bfe_u32 v4, v0, 5, 1
	v_lshl_add_u64 v[2:3], s[34:35], 0, v[132:133]
	v_lshlrev_b32_e32 v132, 8, v6
	v_lshl_add_u64 v[2:3], v[2:3], 0, v[132:133]
	v_lshlrev_b32_e32 v132, 4, v4
	s_add_u32 s54, s34, 0x20b6c000
	v_bfe_u32 v5, v0, 1, 7
	v_lshl_add_u64 v[70:71], v[2:3], 0, v[132:133]
	v_lshrrev_b32_e32 v3, 1, v0
	s_addc_u32 s55, s35, 0
	v_and_b32_e32 v7, 32, v5
	v_lshlrev_b32_e32 v2, 2, v4
	v_and_b32_e32 v3, 64, v3
	s_add_u32 s56, s34, 0x22b6c000
	s_mul_i32 s0, s0, 0x13600
	v_or3_b32 v8, v2, v3, v7
	v_and_b32_e32 v2, 1, v0
	s_addc_u32 s57, s35, 0
	v_and_b32_e32 v68, 63, v0
	s_add_i32 s0, s0, 0
	v_mul_u32_u24_e32 v3, 0x208, v5
	v_mul_u32_u24_e32 v4, 0x104, v2
	v_add3_u32 v69, s0, v3, v4
	v_lshlrev_b32_e32 v198, 6, v2
	v_cmp_eq_u32_e64 s[38:39], 0, v2
	v_cmp_eq_u32_e64 s[40:41], 1, v2
	v_lshlrev_b32_e32 v9, 6, v5
	v_lshrrev_b32_e32 v2, 2, v0
	v_lshlrev_b32_e32 v4, 5, v68
	v_mov_b32_e32 v5, v133
	v_and_b32_e32 v200, 48, v2
	v_lshlrev_b32_e32 v2, 4, v68
	v_mov_b32_e32 v3, v133
	v_lshl_add_u64 v[4:5], s[34:35], 0, v[4:5]
	s_mov_b64 s[24:25], 0x8b6c000
	v_lshl_add_u64 v[72:73], v[4:5], 0, s[24:25]
	v_lshl_add_u64 v[2:3], s[34:35], 0, v[2:3]
	s_mov_b64 s[24:25], 0x2010000
	v_cmp_lt_i32_e32 vcc, v170, v169
	v_lshl_add_u64 v[74:75], v[2:3], 0, s[24:25]
	s_mov_b64 s[24:25], 0x25f6c000
	v_cndmask_b32_e32 v2, v167, v170, vcc
	v_lshlrev_b32_e32 v201, 2, v2
	v_and_b32_e32 v2, 16, v0
	v_cmp_lt_i32_e32 vcc, v171, v169
	v_cmp_eq_u32_e64 s[46:47], 0, v2
	s_add_i32 s20, s0, 0x10400
	v_cndmask_b32_e32 v2, v167, v171, vcc
	v_lshlrev_b32_e32 v202, 2, v2
	v_and_b32_e32 v2, 8, v0
	v_cmp_lt_i32_e32 vcc, v172, v169
	v_cmp_eq_u32_e64 s[48:49], 0, v2
	v_lshlrev_b32_e32 v2, 3, v0
	v_cndmask_b32_e32 v3, v167, v172, vcc
	v_and_or_b32 v2, v2, 56, v168
	v_lshlrev_b32_e32 v203, 2, v3
	v_lshlrev_b32_e32 v208, 2, v2
	v_lshlrev_b32_e32 v2, 2, v68
	v_mov_b32_e32 v3, v133
	v_lshl_add_u64 v[2:3], s[34:35], 0, v[2:3]
	v_lshl_add_u64 v[76:77], v[2:3], 0, s[24:25]
	v_lshlrev_b32_e32 v2, 2, v6
	v_mul_u32_u24_e32 v3, 0x208, v8
	v_add3_u32 v209, s0, v2, v3
	s_mov_b64 s[0:1], 0x2020
	v_lshl_add_u64 v[80:81], v[70:71], 0, s[0:1]
	s_mov_b64 s[0:1], 0x2040
	v_lshl_add_u64 v[82:83], v[70:71], 0, s[0:1]
	s_mov_b64 s[0:1], 0x2060
	v_lshl_add_u64 v[84:85], v[70:71], 0, s[0:1]
	s_mov_b64 s[0:1], 0x2080
	v_lshl_add_u64 v[86:87], v[70:71], 0, s[0:1]
	s_mov_b64 s[0:1], 0x20a0
	v_lshl_add_u64 v[88:89], v[70:71], 0, s[0:1]
	s_mov_b64 s[0:1], 0x20c0
	v_lshl_add_u64 v[90:91], v[70:71], 0, s[0:1]
	s_mov_b64 s[0:1], 0x20e0
	v_lshl_add_u64 v[92:93], v[70:71], 0, s[0:1]
	s_mov_b64 s[0:1], 0x4000
	v_lshl_add_u64 v[94:95], v[70:71], 0, s[0:1]
	s_mov_b64 s[0:1], 0x4020
	v_lshl_add_u64 v[96:97], v[70:71], 0, s[0:1]
	s_mov_b64 s[0:1], 0x4040
	v_lshl_add_u64 v[98:99], v[70:71], 0, s[0:1]
	s_mov_b64 s[0:1], 0x4060
	v_lshl_add_u64 v[100:101], v[70:71], 0, s[0:1]
	s_mov_b64 s[0:1], 0x4080
	v_lshl_add_u64 v[102:103], v[70:71], 0, s[0:1]
	s_mov_b64 s[0:1], 0x40a0
	v_lshl_add_u64 v[104:105], v[70:71], 0, s[0:1]
	s_mov_b64 s[0:1], 0x40c0
	v_lshl_add_u64 v[106:107], v[70:71], 0, s[0:1]
	s_mov_b64 s[0:1], 0x40e0
	v_lshl_add_u64 v[108:109], v[70:71], 0, s[0:1]
	s_mov_b64 s[0:1], 0x6000
	v_lshl_add_u64 v[110:111], v[70:71], 0, s[0:1]
	s_mov_b64 s[0:1], 0x6020
	v_lshl_add_u64 v[112:113], v[70:71], 0, s[0:1]
	s_mov_b64 s[0:1], 0x6040
	v_lshl_add_u64 v[114:115], v[70:71], 0, s[0:1]
	s_mov_b64 s[0:1], 0x6060
	v_lshl_add_u64 v[116:117], v[70:71], 0, s[0:1]
	s_mov_b64 s[0:1], 0x6080
	v_lshl_add_u64 v[118:119], v[70:71], 0, s[0:1]
	s_mov_b64 s[0:1], 0x60a0
	s_add_u32 s58, s34, 0x670c000
	v_cmp_lt_i32_e32 vcc, v173, v169
	v_lshl_add_u64 v[120:121], v[70:71], 0, s[0:1]
	s_mov_b64 s[0:1], 0x60c0
	s_addc_u32 s59, s35, 0
	v_cndmask_b32_e32 v4, v167, v173, vcc
	v_cmp_lt_i32_e32 vcc, v174, v169
	v_lshl_add_u64 v[122:123], v[70:71], 0, s[0:1]
	s_mov_b64 s[0:1], 0x60e0
	s_add_u32 s60, s34, 0x671c000
	v_bfe_u32 v10, v0, 3, 3
	v_cndmask_b32_e32 v5, v167, v174, vcc
	v_cmp_lt_i32_e32 vcc, v175, v169
	v_lshl_add_u64 v[124:125], v[70:71], 0, s[0:1]
	v_lshlrev_b32_e32 v0, 1, v0
	s_movk_i32 s1, 0x100
	v_readlane_b32 s24, v250, 60
	s_addc_u32 s61, s35, 0
	v_cndmask_b32_e32 v11, v167, v175, vcc
	s_lshl_b32 s0, s62, 6
	v_and_or_b32 v132, v0, s1, v132
	v_readlane_b32 s25, v250, 61
	v_cmp_gt_u32_e64 s[42:43], 64, v1
	v_lshl_add_u32 v199, v1, 6, s20
	v_cmp_gt_u32_e64 s[44:45], 32, v68
	v_lshlrev_b32_e32 v204, 2, v4
	v_lshlrev_b32_e32 v205, 2, v5
	v_lshlrev_b32_e32 v206, 2, v11
	v_or_b32_e32 v207, v168, v10
	v_lshl_add_u64 v[78:79], v[70:71], 0, s[70:71]
	v_add_u32_e32 v126, s0, v1
	s_lshl_b32 s64, s63, 6
	v_lshl_add_u64 v[128:129], s[24:25], 0, v[132:133]
	v_or3_b32 v130, s0, v7, v6
	v_add_u32_e32 v132, s20, v9
	s_branch .LBB0_79
